# compression path (32 WGs): block-gather loop (ablk_prep) pipelined 8 deep with the loop-invariant position rows hoisted; frees those CUs earlier for the attention work queue
# speedup vs baseline: 1.0059x; 1.0059x over previous
; DI void ablk_prep_block(const Params& p, int pm) {
;   int tid = threadIdx.x; asm volatile("" : "+v"(tid));
;   const bf16_t* KVC = (const bf16_t*)(p.ws + OFF_KVC); bf16_t* AB = (bf16_t*)(p.ws + OFF_ABLK);
;   const int kv = pm >> 4, bl = pm & 15;
;   for (int idx = tid; idx < 256 * 256; idx += 512) {
;     const int ch = idx & 255, rl = idx >> 8;
;     const int g = rl & 1, n = rl >> 1; const int l = ch >> 3, d0 = (ch & 7) * 8;
;     u32x4 o = {0u, 0u, 0u, 0u};
;     if (n < 127) {
;       const u32x4 v = *(const u32x4*)(KVC + ((size_t)bl * SEQ + 16 * n + l) * 256 + kv * 128 + g * 64 + d0);
;       const float* ps = p.cmp_pos + (kv * 32 + l) * 64 + d0; const f32x4 p0 = *(const f32x4*)ps, p1 = *(const f32x4*)(ps + 4);
; __global__ void __launch_bounds__(512, 2) fwd_mega(Params p) {
;     ...
;     unsigned* qcnt = (unsigned*)(ws + OFF_BAR + 14336) + ck * 128;
;     unsigned* cflag = (unsigned*)(ws + OFF_BAR + 15360) + ck * 64;
;     ...
;     if (bid < 32) {
;       for (int rep = 0; rep < REP_CMP; ++rep) {
;       ablk_prep_block(p, bid);
.LBB0_813:
	s_or_b64 exec, exec, s[8:9]
	s_xor_b64 s[0:1], s[16:17], -1
	v_writelane_b32 v255, s0, 33
	s_lshl_b32 s88, s42, 7
	v_readlane_b32 s2, v254, 13
	v_writelane_b32 v255, s1, 34
	s_lshl_b64 s[0:1], s[88:89], 2
	s_add_u32 s2, s2, s0
	v_readlane_b32 s0, v254, 14
	s_addc_u32 s3, s0, s1
	v_writelane_b32 v255, s2, 35
	s_lshl_b32 s88, s42, 6
	s_lshl_b64 s[0:1], s[88:89], 2
	v_writelane_b32 v255, s3, 36
	v_readlane_b32 s2, v254, 15
	s_add_u32 s8, s2, s0
	v_readlane_b32 s0, v254, 16
	s_addc_u32 s9, s0, s1
	v_readlane_b32 s0, v254, 17
	v_readlane_b32 s1, v254, 18
	s_andn2_b64 vcc, exec, s[0:1]
	s_mov_b64 s[12:13], -1
	s_waitcnt lgkmcnt(0)
	s_barrier
	s_cbranch_vccnz .LBB0_835
	v_mov_b32_e32 v12, v200
	s_mov_b32 s0, 0x10000
	s_nop 0
	v_cmp_gt_i32_e32 vcc, s0, v12
	s_and_saveexec_b64 s[10:11], vcc
	s_cbranch_execz .LBB0_819
	v_bfe_u32 v0, v12, 3, 5
	v_readlane_b32 s0, v254, 19
	v_mov_b32_e32 v2, 4
	v_lshlrev_b32_sdwa v186, v2, v12 dst_sel:DWORD dst_unused:UNUSED_PAD src0_sel:DWORD src1_sel:BYTE_0
	v_or_b32_e32 v4, s0, v0
	v_readlane_b32 s0, v254, 22
	v_mov_b32_e32 v5, v187
	v_lshlrev_b32_e32 v13, 3, v12
	v_lshl_or_b32 v0, v0, 6, s0
	v_readlane_b32 s0, v254, 23
	v_readlane_b32 s1, v254, 24
	v_ashrrev_i32_e32 v1, 31, v0
	s_mov_b64 s[12:13], 0
	v_lshl_add_u64 v[6:7], s[0:1], 0, v[186:187]
	v_readlane_b32 s0, v254, 34
	v_readlane_b32 s2, v254, 36
	v_readlane_b32 s3, v254, 37
	v_readlane_b32 s1, v254, 35
	s_nop 0
	v_lshl_add_u64 v[8:9], v[0:1], 2, s[2:3]
	v_readlane_b32 s0, v254, 20
	v_readlane_b32 s1, v254, 21
	v_lshlrev_b64 v[24:25], 9, v[4:5]
	v_ashrrev_i32_e32 v10, 8, v12
	v_lshl_add_u64 v[24:25], s[0:1], 0, v[24:25]
	v_lshlrev_b32_e32 v22, 7, v10
	v_and_b32_e32 v186, 0x80, v22
	v_lshl_add_u64 v[24:25], v[24:25], 0, v[186:187]
	v_and_b32_e32 v22, 56, v13
	v_lshlrev_b32_e32 v186, 1, v22
	v_lshl_add_u64 v[24:25], v[24:25], 0, v[186:187]
	v_lshlrev_b32_e32 v186, 2, v22
	v_lshl_add_u64 v[60:61], v[8:9], 0, v[186:187]
	global_load_dwordx4 v[14:17], v[60:61], off offset:16
	global_load_dwordx4 v[18:21], v[60:61], off
	v_ashrrev_i32_e32 v11, 31, v10
	v_lshlrev_b64 v[26:27], 12, v[10:11]
	v_lshl_add_u64 v[26:27], v[6:7], 0, v[26:27]
	s_mov_b64 s[14:15], 0x2000
	s_mov_b32 s12, 0
; DI unsigned cvtpk(float lo, float hi) { f32x2_t v = {lo, hi}; bf16x2_t b = __builtin_convertvector(v, bf16x2_t); return __builtin_bit_cast(unsigned, b); }
; DI float bflo(unsigned w) { return __uint_as_float(w << 16); }
; DI float bfhi(unsigned w) { return __uint_as_float(w & 0xffff0000u); }
; DI void ablk_prep_block(const Params& p, int pm) {
;     ...
;   for (int idx = tid; idx < 256 * 256; idx += 512) {
;     const int ch = idx & 255, rl = idx >> 8;
;     const int g = rl & 1, n = rl >> 1; const int l = ch >> 3, d0 = (ch & 7) * 8;
;     u32x4 o = {0u, 0u, 0u, 0u};
;     if (n < 127) {
;       const u32x4 v = *(const u32x4*)(KVC + ((size_t)bl * SEQ + 16 * n + l) * 256 + kv * 128 + g * 64 + d0);
;       const float* ps = p.cmp_pos + (kv * 32 + l) * 64 + d0; const f32x4 p0 = *(const f32x4*)ps, p1 = *(const f32x4*)(ps + 4);
;       o.x = cvtpk(bflo(v.x) + p0[0], bfhi(v.x) + p0[1]); o.y = cvtpk(bflo(v.y) + p0[2], bfhi(v.y) + p0[3]);
;       o.z = cvtpk(bflo(v.z) + p1[0], bfhi(v.z) + p1[1]); o.w = cvtpk(bflo(v.w) + p1[2], bfhi(v.w) + p1[3]);
;     }
;     *(u32x4*)(AB + ((size_t)pm * 256 + rl) * 2048 + ch * 8) = o;
;   }
.Lab_loop:
	s_cmp_eq_u32 s12, 15
	s_cselect_b32 s13, 0, -1
	global_load_dwordx4 v[28:31], v[24:25], off
	v_lshl_add_u64 v[60:61], v[24:25], 0, s[14:15]
	global_load_dwordx4 v[32:35], v[60:61], off
	v_lshl_add_u64 v[60:61], v[60:61], 0, s[14:15]
	global_load_dwordx4 v[36:39], v[60:61], off
	v_lshl_add_u64 v[60:61], v[60:61], 0, s[14:15]
	global_load_dwordx4 v[40:43], v[60:61], off
	v_lshl_add_u64 v[60:61], v[60:61], 0, s[14:15]
	global_load_dwordx4 v[44:47], v[60:61], off
	v_lshl_add_u64 v[60:61], v[60:61], 0, s[14:15]
	global_load_dwordx4 v[48:51], v[60:61], off
	v_lshl_add_u64 v[60:61], v[60:61], 0, s[14:15]
	global_load_dwordx4 v[52:55], v[60:61], off
	v_lshl_add_u64 v[60:61], v[60:61], 0, s[14:15]
	global_load_dwordx4 v[56:59], v[60:61], off
	v_lshl_add_u64 v[24:25], v[60:61], 0, s[14:15]
	s_waitcnt vmcnt(7)
	v_lshlrev_b32_e32 v22, 16, v28
	v_and_b32_e32 v23, 0xffff0000, v28
	v_lshlrev_b32_e32 v64, 16, v29
	v_and_b32_e32 v65, 0xffff0000, v29
	v_pk_add_f32 v[22:23], v[18:19], v[22:23]
	v_pk_add_f32 v[64:65], v[20:21], v[64:65]
	v_lshlrev_b32_e32 v66, 16, v30
	v_and_b32_e32 v67, 0xffff0000, v30
	v_cvt_pk_bf16_f32 v28, v22, v23
	v_cvt_pk_bf16_f32 v29, v64, v65
	v_lshlrev_b32_e32 v22, 16, v31
	v_and_b32_e32 v23, 0xffff0000, v31
	v_pk_add_f32 v[66:67], v[14:15], v[66:67]
	v_pk_add_f32 v[22:23], v[16:17], v[22:23]
	s_nop 0
	v_cvt_pk_bf16_f32 v30, v66, v67
	v_cvt_pk_bf16_f32 v31, v22, v23
	global_store_dwordx4 v[26:27], v[28:31], off
	v_lshl_add_u64 v[26:27], v[26:27], 0, s[14:15]
	s_waitcnt vmcnt(7)
	v_lshlrev_b32_e32 v22, 16, v32
	v_and_b32_e32 v23, 0xffff0000, v32
	v_lshlrev_b32_e32 v64, 16, v33
	v_and_b32_e32 v65, 0xffff0000, v33
	v_pk_add_f32 v[22:23], v[18:19], v[22:23]
	v_pk_add_f32 v[64:65], v[20:21], v[64:65]
	v_lshlrev_b32_e32 v66, 16, v34
	v_and_b32_e32 v67, 0xffff0000, v34
	v_cvt_pk_bf16_f32 v32, v22, v23
	v_cvt_pk_bf16_f32 v33, v64, v65
	v_lshlrev_b32_e32 v22, 16, v35
	v_and_b32_e32 v23, 0xffff0000, v35
	v_pk_add_f32 v[66:67], v[14:15], v[66:67]
	v_pk_add_f32 v[22:23], v[16:17], v[22:23]
	s_nop 0
	v_cvt_pk_bf16_f32 v34, v66, v67
	v_cvt_pk_bf16_f32 v35, v22, v23
	global_store_dwordx4 v[26:27], v[32:35], off
	v_lshl_add_u64 v[26:27], v[26:27], 0, s[14:15]
	s_waitcnt vmcnt(7)
	v_lshlrev_b32_e32 v22, 16, v36
	v_and_b32_e32 v23, 0xffff0000, v36
	v_lshlrev_b32_e32 v64, 16, v37
	v_and_b32_e32 v65, 0xffff0000, v37
	v_pk_add_f32 v[22:23], v[18:19], v[22:23]
	v_pk_add_f32 v[64:65], v[20:21], v[64:65]
	v_lshlrev_b32_e32 v66, 16, v38
	v_and_b32_e32 v67, 0xffff0000, v38
	v_cvt_pk_bf16_f32 v36, v22, v23
	v_cvt_pk_bf16_f32 v37, v64, v65
	v_lshlrev_b32_e32 v22, 16, v39
	v_and_b32_e32 v23, 0xffff0000, v39
	v_pk_add_f32 v[66:67], v[14:15], v[66:67]
	v_pk_add_f32 v[22:23], v[16:17], v[22:23]
	s_nop 0
	v_cvt_pk_bf16_f32 v38, v66, v67
	v_cvt_pk_bf16_f32 v39, v22, v23
	global_store_dwordx4 v[26:27], v[36:39], off
	v_lshl_add_u64 v[26:27], v[26:27], 0, s[14:15]
	s_waitcnt vmcnt(7)
	v_lshlrev_b32_e32 v22, 16, v40
	v_and_b32_e32 v23, 0xffff0000, v40
	v_lshlrev_b32_e32 v64, 16, v41
	v_and_b32_e32 v65, 0xffff0000, v41
	v_pk_add_f32 v[22:23], v[18:19], v[22:23]
	v_pk_add_f32 v[64:65], v[20:21], v[64:65]
	v_lshlrev_b32_e32 v66, 16, v42
	v_and_b32_e32 v67, 0xffff0000, v42
	v_cvt_pk_bf16_f32 v40, v22, v23
	v_cvt_pk_bf16_f32 v41, v64, v65
	v_lshlrev_b32_e32 v22, 16, v43
	v_and_b32_e32 v23, 0xffff0000, v43
	v_pk_add_f32 v[66:67], v[14:15], v[66:67]
	v_pk_add_f32 v[22:23], v[16:17], v[22:23]
	s_nop 0
	v_cvt_pk_bf16_f32 v42, v66, v67
	v_cvt_pk_bf16_f32 v43, v22, v23
	global_store_dwordx4 v[26:27], v[40:43], off
	v_lshl_add_u64 v[26:27], v[26:27], 0, s[14:15]
	s_waitcnt vmcnt(7)
	v_lshlrev_b32_e32 v22, 16, v44
	v_and_b32_e32 v23, 0xffff0000, v44
	v_lshlrev_b32_e32 v64, 16, v45
	v_and_b32_e32 v65, 0xffff0000, v45
	v_pk_add_f32 v[22:23], v[18:19], v[22:23]
	v_pk_add_f32 v[64:65], v[20:21], v[64:65]
	v_lshlrev_b32_e32 v66, 16, v46
	v_and_b32_e32 v67, 0xffff0000, v46
	v_cvt_pk_bf16_f32 v44, v22, v23
	v_cvt_pk_bf16_f32 v45, v64, v65
	v_lshlrev_b32_e32 v22, 16, v47
	v_and_b32_e32 v23, 0xffff0000, v47
	v_pk_add_f32 v[66:67], v[14:15], v[66:67]
	v_pk_add_f32 v[22:23], v[16:17], v[22:23]
	s_nop 0
	v_cvt_pk_bf16_f32 v46, v66, v67
	v_cvt_pk_bf16_f32 v47, v22, v23
	global_store_dwordx4 v[26:27], v[44:47], off
	v_lshl_add_u64 v[26:27], v[26:27], 0, s[14:15]
	s_waitcnt vmcnt(7)
	v_lshlrev_b32_e32 v22, 16, v48
	v_and_b32_e32 v23, 0xffff0000, v48
	v_lshlrev_b32_e32 v64, 16, v49
	v_and_b32_e32 v65, 0xffff0000, v49
	v_pk_add_f32 v[22:23], v[18:19], v[22:23]
	v_pk_add_f32 v[64:65], v[20:21], v[64:65]
	v_lshlrev_b32_e32 v66, 16, v50
	v_and_b32_e32 v67, 0xffff0000, v50
	v_cvt_pk_bf16_f32 v48, v22, v23
	v_cvt_pk_bf16_f32 v49, v64, v65
	v_lshlrev_b32_e32 v22, 16, v51
	v_and_b32_e32 v23, 0xffff0000, v51
	v_pk_add_f32 v[66:67], v[14:15], v[66:67]
	v_pk_add_f32 v[22:23], v[16:17], v[22:23]
	s_nop 0
	v_cvt_pk_bf16_f32 v50, v66, v67
	v_cvt_pk_bf16_f32 v51, v22, v23
	global_store_dwordx4 v[26:27], v[48:51], off
	v_lshl_add_u64 v[26:27], v[26:27], 0, s[14:15]
	s_waitcnt vmcnt(7)
	v_lshlrev_b32_e32 v22, 16, v52
	v_and_b32_e32 v23, 0xffff0000, v52
	v_lshlrev_b32_e32 v64, 16, v53
	v_and_b32_e32 v65, 0xffff0000, v53
	v_pk_add_f32 v[22:23], v[18:19], v[22:23]
	v_pk_add_f32 v[64:65], v[20:21], v[64:65]
	v_lshlrev_b32_e32 v66, 16, v54
	v_and_b32_e32 v67, 0xffff0000, v54
	v_cvt_pk_bf16_f32 v52, v22, v23
	v_cvt_pk_bf16_f32 v53, v64, v65
	v_lshlrev_b32_e32 v22, 16, v55
	v_and_b32_e32 v23, 0xffff0000, v55
	v_pk_add_f32 v[66:67], v[14:15], v[66:67]
	v_pk_add_f32 v[22:23], v[16:17], v[22:23]
	s_nop 0
	v_cvt_pk_bf16_f32 v54, v66, v67
	v_cvt_pk_bf16_f32 v55, v22, v23
	global_store_dwordx4 v[26:27], v[52:55], off
	v_lshl_add_u64 v[26:27], v[26:27], 0, s[14:15]
	s_waitcnt vmcnt(7)
	v_lshlrev_b32_e32 v22, 16, v56
	v_and_b32_e32 v23, 0xffff0000, v56
	v_lshlrev_b32_e32 v64, 16, v57
	v_and_b32_e32 v65, 0xffff0000, v57
	v_pk_add_f32 v[22:23], v[18:19], v[22:23]
	v_pk_add_f32 v[64:65], v[20:21], v[64:65]
	v_lshlrev_b32_e32 v66, 16, v58
	v_and_b32_e32 v67, 0xffff0000, v58
	v_cvt_pk_bf16_f32 v56, v22, v23
	v_cvt_pk_bf16_f32 v57, v64, v65
	v_lshlrev_b32_e32 v22, 16, v59
	v_and_b32_e32 v23, 0xffff0000, v59
	v_pk_add_f32 v[66:67], v[14:15], v[66:67]
	v_pk_add_f32 v[22:23], v[16:17], v[22:23]
	s_nop 0
	v_cvt_pk_bf16_f32 v58, v66, v67
	v_cvt_pk_bf16_f32 v59, v22, v23
	v_and_b32_e32 v56, s13, v56
	v_and_b32_e32 v57, s13, v57
	v_and_b32_e32 v58, s13, v58
	v_and_b32_e32 v59, s13, v59
	global_store_dwordx4 v[26:27], v[56:59], off
	v_lshl_add_u64 v[26:27], v[26:27], 0, s[14:15]
	s_add_i32 s12, s12, 1
	s_cmp_lt_u32 s12, 16
	s_cbranch_scc1 .Lab_loop
